# attention: first V-fragment reads of a step issued at the end of the previous step, ahead of the LDS tile writes
# speedup vs baseline: 1.0043x; 1.0033x over previous
.LBB0_1098:
	s_xor_b64 s[30:31], s[0:1], -1
	s_and_b64 s[0:1], s[0:1], exec
	s_cselect_b32 s1, s19, s37
	v_mov_b32_e32 v174, v190
	s_lshl_b32 s14, s1, 15
	s_lshl_b32 s0, s1, 16
	s_add_u32 s4, s16, s0
	v_readfirstlane_b32 s7, v174
	s_addc_u32 s5, s17, 0
	s_ashr_i32 s0, s7, 6
	v_lshlrev_b32_e32 v1, 3, v174
	s_lshl_b32 s6, s1, 8
	s_lshl_b32 s38, s1, 2
	s_ashr_i32 s1, s0, 31
	v_ashrrev_i32_e32 v0, 4, v174
	v_and_b32_e32 v2, 0x78, v1
	v_and_b32_e32 v175, 31, v174
	v_bfe_u32 v176, v174, 5, 1
	s_lshl_b32 s39, s0, 5
	s_and_b32 s7, s7, 0x3fffffc0
	s_lshl_b64 s[28:29], s[0:1], 13
	v_lshlrev_b32_e32 v2, 1, v2
	v_lshlrev_b32_e32 v3, 8, v0
	v_lshlrev_b32_e32 v10, 8, v175
	v_lshlrev_b32_e32 v11, 4, v176
	s_add_u32 s0, s4, s28
	v_or_b32_e32 v148, v2, v3
	v_or_b32_e32 v12, v11, v10
	s_addc_u32 s1, s5, s29
	global_load_dwordx4 v[96:99], v148, s[22:23]
	global_load_dwordx4 v[100:103], v148, s[20:21]
	global_load_dwordx4 v[136:139], v148, s[42:43]
	global_load_dwordx4 v[140:143], v148, s[26:27]
	global_load_dwordx4 v[104:107], v12, s[0:1]
	global_load_dwordx4 v[108:111], v12, s[0:1] offset:32
	global_load_dwordx4 v[112:115], v12, s[0:1] offset:64
	global_load_dwordx4 v[116:119], v12, s[0:1] offset:96
	global_load_dwordx4 v[120:123], v12, s[0:1] offset:128
	global_load_dwordx4 v[124:127], v12, s[0:1] offset:160
	global_load_dwordx4 v[128:131], v12, s[0:1] offset:192
	global_load_dwordx4 v[132:135], v12, s[0:1] offset:224
	v_and_b32_e32 v6, 0xfffff0, v0
	v_lshlrev_b32_e32 v7, 1, v0
	v_and_or_b32 v6, v7, 8, v6
	v_lshrrev_b32_e32 v7, 1, v0
	v_and_b32_e32 v8, 3, v0
	v_add_u32_e32 v0, 32, v0
	v_and_b32_e32 v4, 63, v174
	v_and_b32_e32 v9, 0xfffff0, v0
	v_lshlrev_b32_e32 v0, 1, v0
	v_lshlrev_b32_e32 v12, 4, v174
	s_lshl_b32 s0, s7, 2
	v_and_or_b32 v0, v0, 8, v9
	v_lshlrev_b32_e32 v9, 3, v4
	v_and_b32_e32 v13, 0xc0, v12
	v_lshlrev_b32_e32 v14, 1, v174
	s_add_i32 s0, s0, 0
	v_lshlrev_b32_e32 v5, 2, v176
	v_and_or_b32 v13, v9, 24, v13
	v_and_b32_e32 v14, 32, v14
	v_and_b32_e32 v9, 0x100, v9
	s_add_i32 s18, s38, 4
	s_add_i32 s39, s39, s6
	s_add_i32 s4, s0, 0x10000
	v_lshrrev_b32_e32 v6, 1, v6
	v_bfe_u32 v1, v1, 5, 2
	v_lshrrev_b32_e32 v0, 1, v0
	v_or3_b32 v9, v13, v14, v9
	v_subrev_u32_e32 v13, s6, v5
	s_cmp_lg_u32 0, -1
	v_or_b32_e32 v6, v6, v1
	v_and_or_b32 v7, v7, 4, v8
	v_or_b32_e32 v0, v0, v1
	v_and_b32_e32 v1, 0x70, v174
	v_cvt_f32_i32_e32 v13, v13
	s_cselect_b32 s0, 0, 0
	v_lshlrev_b32_e32 v6, 9, v6
	v_lshlrev_b32_e32 v7, 6, v7
	v_and_b32_e32 v8, 48, v2
	v_lshlrev_b32_e32 v0, 9, v0
	v_bitop3_b32 v1, v2, v3, v1 bitop3:0xde
	v_add_u32_e32 v178, s0, v9
	s_movk_i32 s0, 0x70
	v_or3_b32 v0, v0, v7, v8
	v_or3_b32 v6, v6, v7, v8
	v_add_u32_e32 v182, 0, v1
	v_bfe_u32 v200, v174, 7, 1
	v_lshlrev_b32_e32 v200, 7, v200
	v_xor_b32_e32 v182, v182, v200
	v_and_b32_e32 v1, 0x70, v12
	v_bitop3_b32 v2, v11, v12, s0 bitop3:0x78
	s_movk_i32 s0, 0x60
	s_waitcnt vmcnt(0)
	v_add_u32_e32 v180, 0, v6
	v_add_u32_e32 v181, 0, v0
	v_add_u32_e32 v0, 0, v10
	v_bitop3_b32 v3, v11, v1, 32 bitop3:0x36
	v_bitop3_b32 v6, v11, v1, 64 bitop3:0x36
	v_bitop3_b32 v1, v11, v1, s0 bitop3:0x36
	v_cmp_gt_u32_e64 s[0:1], 32, v4
	v_or_b32_e32 v4, s39, v175
	v_mov_b32_e32 v32, v149
	v_mov_b32_e32 v33, v149
	v_mov_b32_e32 v46, v149
	v_mov_b32_e32 v47, v149
	v_mul_f32_e32 v179, v172, v13
	v_add_u32_e32 v177, s4, v11
	v_sub_u32_e32 v184, v4, v5
	v_mov_b32_e32 v34, v149
	v_mov_b32_e32 v35, v149
	v_mov_b32_e32 v36, v149
	v_mov_b32_e32 v37, v149
	v_mov_b32_e32 v38, v149
	v_mov_b32_e32 v39, v149
	v_mov_b32_e32 v40, v149
	v_mov_b32_e32 v41, v149
	v_mov_b32_e32 v42, v149
	v_mov_b32_e32 v43, v149
	v_mov_b32_e32 v44, v149
	v_mov_b32_e32 v45, v149
	v_add_u32_e32 v186, v0, v2
	v_add_u32_e32 v187, v0, v3
	v_add_u32_e32 v188, v0, v6
	v_add_u32_e32 v189, v0, v1
	v_bfe_u32 v200, v174, 3, 1
	v_lshlrev_b32_e32 v200, 7, v200
	v_xor_b32_e32 v186, v186, v200
	v_xor_b32_e32 v187, v187, v200
	v_xor_b32_e32 v188, v188, v200
	v_xor_b32_e32 v189, v189, v200
	v_mov_b64_e32 v[62:63], v[46:47]
	v_mov_b64_e32 v[16:17], v[32:33]
	v_mov_b64_e32 v[0:1], v[32:33]
	s_mov_b32 s12, 0
	v_lshl_add_u32 v183, v175, 2, s4
	v_mov_b32_e32 v203, 0xf149f2ca
	v_mov_b32_e32 v185, 0
	s_movk_i32 s13, 0x7f
	s_mov_b64 s[46:47], s[2:3]
	s_mov_b64 s[40:41], s[24:25]
	v_mov_b64_e32 v[60:61], v[44:45]
	v_mov_b64_e32 v[58:59], v[42:43]
	v_mov_b64_e32 v[56:57], v[40:41]
	v_mov_b64_e32 v[54:55], v[38:39]
	v_mov_b64_e32 v[52:53], v[36:37]
	v_mov_b64_e32 v[50:51], v[34:35]
	v_mov_b64_e32 v[48:49], v[32:33]
	v_mov_b64_e32 v[18:19], v[34:35]
	v_mov_b64_e32 v[20:21], v[36:37]
	v_mov_b64_e32 v[22:23], v[38:39]
	v_mov_b64_e32 v[24:25], v[40:41]
	v_mov_b64_e32 v[26:27], v[42:43]
	v_mov_b64_e32 v[28:29], v[44:45]
	v_mov_b64_e32 v[30:31], v[46:47]
	v_mov_b64_e32 v[2:3], v[34:35]
	v_mov_b64_e32 v[4:5], v[36:37]
	v_mov_b64_e32 v[6:7], v[38:39]
	v_mov_b64_e32 v[8:9], v[40:41]
	v_mov_b64_e32 v[10:11], v[42:43]
	v_mov_b64_e32 v[12:13], v[44:45]
	v_mov_b64_e32 v[14:15], v[46:47]
	s_waitcnt vmcnt(11)
	ds_write_b128 v180, v[96:99]
	s_waitcnt vmcnt(10)
	ds_write_b128 v181, v[100:103]
	s_waitcnt vmcnt(9)
	ds_write_b128 v182, v[136:139] offset:32768
	s_waitcnt vmcnt(8)
	ds_write_b128 v182, v[140:143] offset:40960
	s_waitcnt lgkmcnt(0)
	s_barrier
	v_add_u32_e32 v168, 0x4000, v148
	global_load_dwordx4 v[136:139], v168, s[42:43]
	global_load_dwordx4 v[140:143], v168, s[26:27]
	v_add_u32_e32 v169, 0x4000, v168
	s_mov_b32 s13, 0
	s_mov_b32 s12, 0
	s_mov_b32 s10, 0x3e0293ee
	s_mov_b32 s6, 0x11000
	s_mov_b32 s7, 0
	s_mov_b32 s8, 0x4000
	ds_read_b128 v[236:239], v186 offset:32768
	ds_read_b128 v[240:243], v186 offset:40960
	v_mov_b32_e32 v244, 0
	v_mov_b32_e32 v245, 0
	v_mov_b32_e32 v246, 0
	v_mov_b32_e32 v247, 0
	v_add_u32_e32 v200, s6, v180
	v_add_u32_e32 v201, s6, v181
	ds_write_b128 v200, v[244:247]
	ds_write_b128 v201, v[244:247]
	v_mov_b32_e32 v204, 0
	v_mov_b32_e32 v205, 0
	v_mov_b32_e32 v206, 0
	v_mov_b32_e32 v207, 0
	v_mov_b32_e32 v208, 0
	v_mov_b32_e32 v209, 0
	v_mov_b32_e32 v210, 0
	v_mov_b32_e32 v211, 0
	v_mov_b32_e32 v212, 0
	v_mov_b32_e32 v213, 0
	v_mov_b32_e32 v214, 0
	v_mov_b32_e32 v215, 0
	v_mov_b32_e32 v216, 0
	v_mov_b32_e32 v217, 0
	v_mov_b32_e32 v218, 0
	v_mov_b32_e32 v219, 0
	v_cvt_f32_u32_e32 v64, s13
	v_mov_b32_e32 v165, v164
	v_fma_f32 v64, v172, v64, v179
	v_add_f32_e32 v68, v173, v64
	v_add_f32_e32 v72, v173, v68
	v_add_f32_e32 v76, v173, v72
	v_add_f32_e32 v65, v172, v64
	v_add_f32_e32 v69, v172, v68
	v_add_f32_e32 v73, v172, v72
	v_add_f32_e32 v77, v172, v76
	v_pk_add_f32 v[66:67], v[162:163], v[64:65] op_sel_hi:[1,0]
	v_pk_add_f32 v[70:71], v[162:163], v[68:69] op_sel_hi:[1,0]
	v_pk_add_f32 v[74:75], v[162:163], v[72:73] op_sel_hi:[1,0]
	v_pk_add_f32 v[78:79], v[162:163], v[76:77] op_sel_hi:[1,0]
	v_pk_add_f32 v[82:83], v[164:165], v[66:67]
	v_pk_add_f32 v[80:81], v[166:167], v[64:65]
	v_pk_add_f32 v[86:87], v[164:165], v[70:71]
	v_pk_add_f32 v[84:85], v[164:165], v[68:69]
	v_pk_add_f32 v[90:91], v[164:165], v[74:75]
	v_pk_add_f32 v[88:89], v[164:165], v[72:73]
	v_pk_add_f32 v[94:95], v[164:165], v[78:79]
	v_pk_add_f32 v[92:93], v[164:165], v[76:77]
	s_addk_i32 s13, 0x40
	s_waitcnt lgkmcnt(3)
	v_mfma_f32_32x32x16_bf16 v[64:79], v[236:239], v[104:107], v[64:79]
	ds_read_b128 v[236:239], v187 offset:32768
	s_waitcnt lgkmcnt(3)
	v_mfma_f32_32x32x16_bf16 v[80:95], v[240:243], v[104:107], v[80:95]
	ds_read_b128 v[240:243], v187 offset:40960
	s_waitcnt lgkmcnt(1)
	v_mfma_f32_32x32x16_bf16 v[64:79], v[236:239], v[108:111], v[64:79]
	ds_read_b128 v[236:239], v188 offset:32768
	s_waitcnt lgkmcnt(1)
	v_mfma_f32_32x32x16_bf16 v[80:95], v[240:243], v[108:111], v[80:95]
	ds_read_b128 v[240:243], v188 offset:40960
	s_waitcnt lgkmcnt(1)
	v_mfma_f32_32x32x16_bf16 v[64:79], v[236:239], v[112:115], v[64:79]
	ds_read_b128 v[236:239], v189 offset:32768
	s_waitcnt lgkmcnt(1)
	v_mfma_f32_32x32x16_bf16 v[80:95], v[240:243], v[112:115], v[80:95]
	ds_read_b128 v[240:243], v189 offset:40960
	s_waitcnt lgkmcnt(1)
	v_mfma_f32_32x32x16_bf16 v[64:79], v[236:239], v[116:119], v[64:79]
	v_xor_b32_e32 v186, 0x80, v186
	v_xor_b32_e32 v187, 0x80, v187
	v_xor_b32_e32 v188, 0x80, v188
	v_xor_b32_e32 v189, 0x80, v189
	ds_read_b128 v[236:239], v186 offset:32768
	s_waitcnt lgkmcnt(1)
	v_mfma_f32_32x32x16_bf16 v[80:95], v[240:243], v[116:119], v[80:95]
	ds_read_b128 v[240:243], v186 offset:40960
	s_waitcnt lgkmcnt(1)
	v_mfma_f32_32x32x16_bf16 v[64:79], v[236:239], v[120:123], v[64:79]
	ds_read_b128 v[236:239], v187 offset:32768
	s_waitcnt lgkmcnt(1)
	v_mfma_f32_32x32x16_bf16 v[80:95], v[240:243], v[120:123], v[80:95]
	ds_read_b128 v[240:243], v187 offset:40960
	s_waitcnt lgkmcnt(1)
	v_mfma_f32_32x32x16_bf16 v[64:79], v[236:239], v[124:127], v[64:79]
	ds_read_b128 v[236:239], v188 offset:32768
	s_waitcnt lgkmcnt(1)
	v_mfma_f32_32x32x16_bf16 v[80:95], v[240:243], v[124:127], v[80:95]
	ds_read_b128 v[240:243], v188 offset:40960
	s_waitcnt lgkmcnt(1)
	v_mfma_f32_32x32x16_bf16 v[64:79], v[236:239], v[128:131], v[64:79]
	ds_read_b128 v[236:239], v189 offset:32768
	s_waitcnt lgkmcnt(1)
	v_mfma_f32_32x32x16_bf16 v[80:95], v[240:243], v[128:131], v[80:95]
	ds_read_b128 v[240:243], v189 offset:40960
	s_waitcnt lgkmcnt(1)
	v_mfma_f32_32x32x16_bf16 v[64:79], v[236:239], v[132:135], v[64:79]
	s_waitcnt lgkmcnt(0)
	v_mfma_f32_32x32x16_bf16 v[80:95], v[240:243], v[132:135], v[80:95]
	s_waitcnt vmcnt(0)
	ds_write_b128 v182, v[136:139] offset:49152
	ds_write_b128 v182, v[140:143] offset:57344
	s_waitcnt lgkmcnt(0)
	s_barrier
	v_add_u32_e32 v165, s6, v178
	ds_read_b64_tr_b16 v[220:221], v165 offset:0
	ds_read_b64_tr_b16 v[222:223], v165 offset:2048
	ds_read_b64_tr_b16 v[224:225], v165 offset:4096
	ds_read_b64_tr_b16 v[226:227], v165 offset:6144
	ds_read_b64_tr_b16 v[228:229], v165 offset:8192
	ds_read_b64_tr_b16 v[230:231], v165 offset:10240
	ds_read_b64_tr_b16 v[232:233], v165 offset:12288
	ds_read_b64_tr_b16 v[234:235], v165 offset:14336
	.p2alignl 6, 3212836864

.Lat_nle:
	v_add_u32_e32 v168, 0x4000, v168
	v_add_u32_e32 v169, 0x4000, v169
	s_add_i32 s5, s13, -1
	s_cmp_gt_i32 s5, s39
	s_cselect_b64 s[46:47], -1, 0
	s_and_b64 vcc, exec, s[46:47]
	s_cbranch_vccz .Lat_nme
	v_cmp_gt_i32_e64 s[48:49], 0, v184
	v_cmp_gt_i32_e64 s[50:51], 1, v184
	v_cmp_gt_i32_e64 s[52:53], 2, v184
	v_cmp_gt_i32_e64 s[54:55], 3, v184
	v_cmp_gt_i32_e64 s[56:57], 8, v184
	v_cmp_gt_i32_e64 s[58:59], 9, v184
	v_cmp_gt_i32_e64 s[60:61], 10, v184
	v_cmp_gt_i32_e64 s[62:63], 11, v184
	v_cndmask_b32_e64 v64, v64, v198, s[48:49]
	v_cndmask_b32_e64 v65, v65, v198, s[50:51]
	v_cndmask_b32_e64 v66, v66, v198, s[52:53]
	v_cndmask_b32_e64 v67, v67, v198, s[54:55]
	v_cndmask_b32_e64 v68, v68, v198, s[56:57]
	v_cndmask_b32_e64 v69, v69, v198, s[58:59]
	v_cndmask_b32_e64 v70, v70, v198, s[60:61]
	v_cndmask_b32_e64 v71, v71, v198, s[62:63]
	v_cmp_gt_i32_e64 s[48:49], 16, v184
	v_cmp_gt_i32_e64 s[50:51], 17, v184
	v_cmp_gt_i32_e64 s[52:53], 18, v184
	v_cmp_gt_i32_e64 s[54:55], 19, v184
	v_cmp_gt_i32_e64 s[56:57], 24, v184
	v_cmp_gt_i32_e64 s[58:59], 25, v184
	v_cmp_gt_i32_e64 s[60:61], 26, v184
	v_cmp_gt_i32_e64 s[62:63], 27, v184
	v_cndmask_b32_e64 v72, v72, v198, s[48:49]
	v_cndmask_b32_e64 v73, v73, v198, s[50:51]
	v_cndmask_b32_e64 v74, v74, v198, s[52:53]
	v_cndmask_b32_e64 v75, v75, v198, s[54:55]
	v_cndmask_b32_e64 v76, v76, v198, s[56:57]
	v_cndmask_b32_e64 v77, v77, v198, s[58:59]
	v_cndmask_b32_e64 v78, v78, v198, s[60:61]
	v_cndmask_b32_e64 v79, v79, v198, s[62:63]
	v_cmp_gt_i32_e64 s[48:49], 32, v184
	v_cmp_gt_i32_e64 s[50:51], 33, v184
	v_cmp_gt_i32_e64 s[52:53], 34, v184
	v_cmp_gt_i32_e64 s[54:55], 35, v184
	v_cmp_gt_i32_e64 s[56:57], 40, v184
	v_cmp_gt_i32_e64 s[58:59], 41, v184
	v_cmp_gt_i32_e64 s[60:61], 42, v184
	v_cmp_gt_i32_e64 s[62:63], 43, v184
	v_cndmask_b32_e64 v80, v80, v198, s[48:49]
	v_cndmask_b32_e64 v81, v81, v198, s[50:51]
	v_cndmask_b32_e64 v82, v82, v198, s[52:53]
	v_cndmask_b32_e64 v83, v83, v198, s[54:55]
	v_cndmask_b32_e64 v84, v84, v198, s[56:57]
	v_cndmask_b32_e64 v85, v85, v198, s[58:59]
	v_cndmask_b32_e64 v86, v86, v198, s[60:61]
	v_cndmask_b32_e64 v87, v87, v198, s[62:63]
	v_cmp_gt_i32_e64 s[48:49], 48, v184
	v_cmp_gt_i32_e64 s[50:51], 49, v184
	v_cmp_gt_i32_e64 s[52:53], 50, v184
	v_cmp_gt_i32_e64 s[54:55], 51, v184
	v_cmp_gt_i32_e64 s[56:57], 56, v184
	v_cmp_gt_i32_e64 s[58:59], 57, v184
	v_cmp_gt_i32_e64 s[60:61], 58, v184
	v_cmp_gt_i32_e64 s[62:63], 59, v184
	v_cndmask_b32_e64 v88, v88, v198, s[48:49]
	v_cndmask_b32_e64 v89, v89, v198, s[50:51]
	v_cndmask_b32_e64 v90, v90, v198, s[52:53]
	v_cndmask_b32_e64 v91, v91, v198, s[54:55]
	v_cndmask_b32_e64 v92, v92, v198, s[56:57]
	v_cndmask_b32_e64 v93, v93, v198, s[58:59]
	v_cndmask_b32_e64 v94, v94, v198, s[60:61]
	v_cndmask_b32_e64 v95, v95, v198, s[62:63]

.Lat_nre:
	s_waitcnt lgkmcnt(0)
	s_barrier
	v_xor_b32_e32 v186, 0x80, v186
	v_xor_b32_e32 v187, 0x80, v187
	v_xor_b32_e32 v188, 0x80, v188
	v_xor_b32_e32 v189, 0x80, v189
	ds_read_b128 v[236:239], v186 offset:49152
	ds_read_b128 v[240:243], v186 offset:57344
	v_cvt_f32_u32_e32 v204, s13
	v_mov_b32_e32 v165, v164
	v_fma_f32 v204, v172, v204, v179
	v_add_f32_e32 v208, v173, v204
	v_add_f32_e32 v212, v173, v208
	v_add_f32_e32 v216, v173, v212
	v_add_f32_e32 v205, v172, v204
	v_add_f32_e32 v209, v172, v208
	v_add_f32_e32 v213, v172, v212
	v_add_f32_e32 v217, v172, v216
	v_pk_add_f32 v[206:207], v[162:163], v[204:205] op_sel_hi:[1,0]
	v_pk_add_f32 v[210:211], v[162:163], v[208:209] op_sel_hi:[1,0]
	v_pk_add_f32 v[214:215], v[162:163], v[212:213] op_sel_hi:[1,0]
	v_pk_add_f32 v[218:219], v[162:163], v[216:217] op_sel_hi:[1,0]
	v_pk_add_f32 v[222:223], v[164:165], v[206:207]
	v_pk_add_f32 v[220:221], v[166:167], v[204:205]
	v_pk_add_f32 v[226:227], v[164:165], v[210:211]
	v_pk_add_f32 v[224:225], v[164:165], v[208:209]
	v_pk_add_f32 v[230:231], v[164:165], v[214:215]
	v_pk_add_f32 v[228:229], v[164:165], v[212:213]
	v_pk_add_f32 v[234:235], v[164:165], v[218:219]
	v_pk_add_f32 v[232:233], v[164:165], v[216:217]
	s_addk_i32 s13, 0x40
	v_exp_f32_e32 v80, v80
	s_waitcnt lgkmcnt(1)
	v_mfma_f32_32x32x16_bf16 v[204:219], v[236:239], v[104:107], v[204:219]
	ds_read_b128 v[236:239], v187 offset:49152
	v_exp_f32_e32 v81, v81
	v_pk_add_f32 v[170:171], v[170:171], v[78:79]
	v_exp_f32_e32 v82, v82
	s_waitcnt lgkmcnt(1)
	v_mfma_f32_32x32x16_bf16 v[220:235], v[240:243], v[104:107], v[220:235]
	ds_read_b128 v[240:243], v187 offset:57344
	v_exp_f32_e32 v83, v83
	v_pk_add_f32 v[170:171], v[170:171], v[80:81]
	v_exp_f32_e32 v84, v84
	v_exp_f32_e32 v85, v85
	s_waitcnt lgkmcnt(1)
	v_mfma_f32_32x32x16_bf16 v[204:219], v[236:239], v[108:111], v[204:219]
	ds_read_b128 v[236:239], v188 offset:49152
	v_pk_add_f32 v[170:171], v[170:171], v[82:83]
	v_exp_f32_e32 v86, v86
	v_exp_f32_e32 v87, v87
	s_waitcnt lgkmcnt(1)
	v_mfma_f32_32x32x16_bf16 v[220:235], v[240:243], v[108:111], v[220:235]
	ds_read_b128 v[240:243], v188 offset:57344
	v_pk_add_f32 v[170:171], v[170:171], v[84:85]
	v_exp_f32_e32 v88, v88
	v_exp_f32_e32 v89, v89
	v_pk_add_f32 v[170:171], v[170:171], v[86:87]
	s_waitcnt lgkmcnt(1)
	v_mfma_f32_32x32x16_bf16 v[204:219], v[236:239], v[112:115], v[204:219]
	ds_read_b128 v[236:239], v189 offset:49152
	v_exp_f32_e32 v90, v90
	v_exp_f32_e32 v91, v91
	v_pk_add_f32 v[170:171], v[170:171], v[88:89]
	v_exp_f32_e32 v92, v92
	s_waitcnt lgkmcnt(1)
	v_mfma_f32_32x32x16_bf16 v[220:235], v[240:243], v[112:115], v[220:235]
	ds_read_b128 v[240:243], v189 offset:57344
	v_exp_f32_e32 v93, v93
	v_pk_add_f32 v[170:171], v[170:171], v[90:91]
	v_exp_f32_e32 v94, v94
	s_waitcnt lgkmcnt(1)
	v_mfma_f32_32x32x16_bf16 v[204:219], v[236:239], v[116:119], v[204:219]
	v_xor_b32_e32 v186, 0x80, v186
	v_xor_b32_e32 v187, 0x80, v187
	v_xor_b32_e32 v188, 0x80, v188
	v_xor_b32_e32 v189, 0x80, v189
	ds_read_b128 v[236:239], v186 offset:49152
	v_exp_f32_e32 v95, v95
	v_pk_add_f32 v[170:171], v[170:171], v[92:93]
	s_nop 0
	v_pk_add_f32 v[170:171], v[170:171], v[94:95]
	s_waitcnt lgkmcnt(1)
	v_mfma_f32_32x32x16_bf16 v[220:235], v[240:243], v[116:119], v[220:235]
	ds_read_b128 v[240:243], v186 offset:57344
	v_add_f32_e32 v249, v170, v171
	v_mov_b32_e32 v170, v249
	s_nop 1
	s_waitcnt lgkmcnt(1)
	v_mfma_f32_32x32x16_bf16 v[204:219], v[236:239], v[120:123], v[204:219]
	ds_read_b128 v[236:239], v187 offset:49152
	v_permlane32_swap_b32_e32 v249, v170
	v_cvt_pk_bf16_f32 v64, v64, v65
	v_cvt_pk_bf16_f32 v65, v66, v67
	v_cvt_pk_bf16_f32 v66, v68, v69
	s_waitcnt lgkmcnt(1)
	v_mfma_f32_32x32x16_bf16 v[220:235], v[240:243], v[120:123], v[220:235]
	ds_read_b128 v[240:243], v187 offset:57344
	v_cvt_pk_bf16_f32 v67, v70, v71
	v_cvt_pk_bf16_f32 v68, v72, v73
	v_cvt_pk_bf16_f32 v69, v74, v75
	s_waitcnt lgkmcnt(1)
	v_mfma_f32_32x32x16_bf16 v[204:219], v[236:239], v[124:127], v[204:219]
	ds_read_b128 v[236:239], v188 offset:49152
	v_cvt_pk_bf16_f32 v70, v76, v77
	v_cvt_pk_bf16_f32 v71, v78, v79
	v_cvt_pk_bf16_f32 v72, v80, v81
	v_cvt_pk_bf16_f32 v73, v82, v83
	s_waitcnt lgkmcnt(1)
	v_mfma_f32_32x32x16_bf16 v[220:235], v[240:243], v[124:127], v[220:235]
	ds_read_b128 v[240:243], v188 offset:57344
	v_cvt_pk_bf16_f32 v74, v84, v85
	v_cvt_pk_bf16_f32 v75, v86, v87
	v_cvt_pk_bf16_f32 v76, v88, v89
	s_waitcnt lgkmcnt(1)
	v_mfma_f32_32x32x16_bf16 v[204:219], v[236:239], v[128:131], v[204:219]
	ds_read_b128 v[236:239], v189 offset:49152
	v_cvt_pk_bf16_f32 v77, v90, v91
	v_cvt_pk_bf16_f32 v78, v92, v93
	v_cvt_pk_bf16_f32 v79, v94, v95
	v_add_u32_e32 v165, s7, v178
	ds_read_b64_tr_b16 v[80:81], v165 offset:0
	ds_read_b64_tr_b16 v[82:83], v165 offset:2048
	ds_read_b64_tr_b16 v[84:85], v165 offset:4096
	ds_read_b64_tr_b16 v[86:87], v165 offset:6144
	ds_read_b64_tr_b16 v[88:89], v165 offset:8192
	ds_read_b64_tr_b16 v[90:91], v165 offset:10240
	ds_read_b64_tr_b16 v[92:93], v165 offset:12288
	ds_read_b64_tr_b16 v[94:95], v165 offset:14336
	v_permlane32_swap_b32_e32 v64, v66
	s_waitcnt lgkmcnt(1)
	v_mfma_f32_32x32x16_bf16 v[220:235], v[240:243], v[128:131], v[220:235]
	ds_read_b128 v[240:243], v189 offset:57344
	v_permlane32_swap_b32_e32 v65, v67
	v_permlane32_swap_b32_e32 v68, v70
	v_permlane32_swap_b32_e32 v69, v71
	v_permlane32_swap_b32_e32 v72, v74
	s_waitcnt lgkmcnt(1)
	v_mfma_f32_32x32x16_bf16 v[204:219], v[236:239], v[132:135], v[204:219]
	v_permlane32_swap_b32_e32 v73, v75
	v_permlane32_swap_b32_e32 v76, v78
	v_permlane32_swap_b32_e32 v77, v79
	s_waitcnt lgkmcnt(0)
	v_mfma_f32_32x32x16_bf16 v[220:235], v[240:243], v[132:135], v[220:235]
	v_add_f32_e32 v171, v249, v170
	v_fmac_f32_e32 v171, v185, v202
	v_mov_b32_e32 v185, v171
	s_waitcnt vmcnt(0)
	v_add_u32_e32 v200, s8, v180
	v_add_u32_e32 v201, s8, v181
	ds_write_b128 v200, v[96:99]
	ds_write_b128 v201, v[100:103]
	s_and_b64 vcc, exec, s[34:35]
	s_cbranch_vccz .Lat_nwe
	ds_write_b128 v182, v[136:139] offset:32768
	ds_write_b128 v182, v[140:143] offset:40960

.Lat_nlo:
	v_add_u32_e32 v168, 0x4000, v168
	v_add_u32_e32 v169, 0x4000, v169
	s_add_i32 s5, s13, -1
	s_cmp_gt_i32 s5, s39
	s_cselect_b64 s[46:47], -1, 0
	s_and_b64 vcc, exec, s[46:47]
	s_cbranch_vccz .Lat_nmo
	v_cmp_gt_i32_e64 s[48:49], 0, v184
	v_cmp_gt_i32_e64 s[50:51], 1, v184
	v_cmp_gt_i32_e64 s[52:53], 2, v184
	v_cmp_gt_i32_e64 s[54:55], 3, v184
	v_cmp_gt_i32_e64 s[56:57], 8, v184
	v_cmp_gt_i32_e64 s[58:59], 9, v184
	v_cmp_gt_i32_e64 s[60:61], 10, v184
	v_cmp_gt_i32_e64 s[62:63], 11, v184
	v_cndmask_b32_e64 v204, v204, v198, s[48:49]
	v_cndmask_b32_e64 v205, v205, v198, s[50:51]
	v_cndmask_b32_e64 v206, v206, v198, s[52:53]
	v_cndmask_b32_e64 v207, v207, v198, s[54:55]
	v_cndmask_b32_e64 v208, v208, v198, s[56:57]
	v_cndmask_b32_e64 v209, v209, v198, s[58:59]
	v_cndmask_b32_e64 v210, v210, v198, s[60:61]
	v_cndmask_b32_e64 v211, v211, v198, s[62:63]
	v_cmp_gt_i32_e64 s[48:49], 16, v184
	v_cmp_gt_i32_e64 s[50:51], 17, v184
	v_cmp_gt_i32_e64 s[52:53], 18, v184
	v_cmp_gt_i32_e64 s[54:55], 19, v184
	v_cmp_gt_i32_e64 s[56:57], 24, v184
	v_cmp_gt_i32_e64 s[58:59], 25, v184
	v_cmp_gt_i32_e64 s[60:61], 26, v184
	v_cmp_gt_i32_e64 s[62:63], 27, v184
	v_cndmask_b32_e64 v212, v212, v198, s[48:49]
	v_cndmask_b32_e64 v213, v213, v198, s[50:51]
	v_cndmask_b32_e64 v214, v214, v198, s[52:53]
	v_cndmask_b32_e64 v215, v215, v198, s[54:55]
	v_cndmask_b32_e64 v216, v216, v198, s[56:57]
	v_cndmask_b32_e64 v217, v217, v198, s[58:59]
	v_cndmask_b32_e64 v218, v218, v198, s[60:61]
	v_cndmask_b32_e64 v219, v219, v198, s[62:63]
	v_cmp_gt_i32_e64 s[48:49], 32, v184
	v_cmp_gt_i32_e64 s[50:51], 33, v184
	v_cmp_gt_i32_e64 s[52:53], 34, v184
	v_cmp_gt_i32_e64 s[54:55], 35, v184
	v_cmp_gt_i32_e64 s[56:57], 40, v184
	v_cmp_gt_i32_e64 s[58:59], 41, v184
	v_cmp_gt_i32_e64 s[60:61], 42, v184
	v_cmp_gt_i32_e64 s[62:63], 43, v184
	v_cndmask_b32_e64 v220, v220, v198, s[48:49]
	v_cndmask_b32_e64 v221, v221, v198, s[50:51]
	v_cndmask_b32_e64 v222, v222, v198, s[52:53]
	v_cndmask_b32_e64 v223, v223, v198, s[54:55]
	v_cndmask_b32_e64 v224, v224, v198, s[56:57]
	v_cndmask_b32_e64 v225, v225, v198, s[58:59]
	v_cndmask_b32_e64 v226, v226, v198, s[60:61]
	v_cndmask_b32_e64 v227, v227, v198, s[62:63]
	v_cmp_gt_i32_e64 s[48:49], 48, v184
	v_cmp_gt_i32_e64 s[50:51], 49, v184
	v_cmp_gt_i32_e64 s[52:53], 50, v184
	v_cmp_gt_i32_e64 s[54:55], 51, v184
	v_cmp_gt_i32_e64 s[56:57], 56, v184
	v_cmp_gt_i32_e64 s[58:59], 57, v184
	v_cmp_gt_i32_e64 s[60:61], 58, v184
	v_cmp_gt_i32_e64 s[62:63], 59, v184
	v_cndmask_b32_e64 v228, v228, v198, s[48:49]
	v_cndmask_b32_e64 v229, v229, v198, s[50:51]
	v_cndmask_b32_e64 v230, v230, v198, s[52:53]
	v_cndmask_b32_e64 v231, v231, v198, s[54:55]
	v_cndmask_b32_e64 v232, v232, v198, s[56:57]
	v_cndmask_b32_e64 v233, v233, v198, s[58:59]
	v_cndmask_b32_e64 v234, v234, v198, s[60:61]
	v_cndmask_b32_e64 v235, v235, v198, s[62:63]

.Lat_nro:
	s_waitcnt lgkmcnt(0)
	s_barrier
	v_xor_b32_e32 v186, 0x80, v186
	v_xor_b32_e32 v187, 0x80, v187
	v_xor_b32_e32 v188, 0x80, v188
	v_xor_b32_e32 v189, 0x80, v189
	ds_read_b128 v[236:239], v186 offset:32768
	ds_read_b128 v[240:243], v186 offset:40960
	v_cvt_f32_u32_e32 v64, s13
	v_mov_b32_e32 v165, v164
	v_fma_f32 v64, v172, v64, v179
	v_add_f32_e32 v68, v173, v64
	v_add_f32_e32 v72, v173, v68
	v_add_f32_e32 v76, v173, v72
	v_add_f32_e32 v65, v172, v64
	v_add_f32_e32 v69, v172, v68
	v_add_f32_e32 v73, v172, v72
	v_add_f32_e32 v77, v172, v76
	v_pk_add_f32 v[66:67], v[162:163], v[64:65] op_sel_hi:[1,0]
	v_pk_add_f32 v[70:71], v[162:163], v[68:69] op_sel_hi:[1,0]
	v_pk_add_f32 v[74:75], v[162:163], v[72:73] op_sel_hi:[1,0]
	v_pk_add_f32 v[78:79], v[162:163], v[76:77] op_sel_hi:[1,0]
	v_pk_add_f32 v[82:83], v[164:165], v[66:67]
	v_pk_add_f32 v[80:81], v[166:167], v[64:65]
	v_pk_add_f32 v[86:87], v[164:165], v[70:71]
	v_pk_add_f32 v[84:85], v[164:165], v[68:69]
	v_pk_add_f32 v[90:91], v[164:165], v[74:75]
	v_pk_add_f32 v[88:89], v[164:165], v[72:73]
	v_pk_add_f32 v[94:95], v[164:165], v[78:79]
	v_pk_add_f32 v[92:93], v[164:165], v[76:77]
	s_addk_i32 s13, 0x40
	v_exp_f32_e32 v220, v220
	s_waitcnt lgkmcnt(1)
	v_mfma_f32_32x32x16_bf16 v[64:79], v[236:239], v[104:107], v[64:79]
	ds_read_b128 v[236:239], v187 offset:32768
	v_exp_f32_e32 v221, v221
	v_pk_add_f32 v[170:171], v[170:171], v[218:219]
	v_exp_f32_e32 v222, v222
	s_waitcnt lgkmcnt(1)
	v_mfma_f32_32x32x16_bf16 v[80:95], v[240:243], v[104:107], v[80:95]
	ds_read_b128 v[240:243], v187 offset:40960
	v_exp_f32_e32 v223, v223
	v_pk_add_f32 v[170:171], v[170:171], v[220:221]
	v_exp_f32_e32 v224, v224
	v_exp_f32_e32 v225, v225
	s_waitcnt lgkmcnt(1)
	v_mfma_f32_32x32x16_bf16 v[64:79], v[236:239], v[108:111], v[64:79]
	ds_read_b128 v[236:239], v188 offset:32768
	v_pk_add_f32 v[170:171], v[170:171], v[222:223]
	v_exp_f32_e32 v226, v226
	v_exp_f32_e32 v227, v227
	s_waitcnt lgkmcnt(1)
	v_mfma_f32_32x32x16_bf16 v[80:95], v[240:243], v[108:111], v[80:95]
	ds_read_b128 v[240:243], v188 offset:40960
	v_pk_add_f32 v[170:171], v[170:171], v[224:225]
	v_exp_f32_e32 v228, v228
	v_exp_f32_e32 v229, v229
	v_pk_add_f32 v[170:171], v[170:171], v[226:227]
	s_waitcnt lgkmcnt(1)
	v_mfma_f32_32x32x16_bf16 v[64:79], v[236:239], v[112:115], v[64:79]
	ds_read_b128 v[236:239], v189 offset:32768
	v_exp_f32_e32 v230, v230
	v_exp_f32_e32 v231, v231
	v_pk_add_f32 v[170:171], v[170:171], v[228:229]
	v_exp_f32_e32 v232, v232
	s_waitcnt lgkmcnt(1)
	v_mfma_f32_32x32x16_bf16 v[80:95], v[240:243], v[112:115], v[80:95]
	ds_read_b128 v[240:243], v189 offset:40960
	v_exp_f32_e32 v233, v233
	v_pk_add_f32 v[170:171], v[170:171], v[230:231]
	v_exp_f32_e32 v234, v234
	s_waitcnt lgkmcnt(1)
	v_mfma_f32_32x32x16_bf16 v[64:79], v[236:239], v[116:119], v[64:79]
	v_xor_b32_e32 v186, 0x80, v186
	v_xor_b32_e32 v187, 0x80, v187
	v_xor_b32_e32 v188, 0x80, v188
	v_xor_b32_e32 v189, 0x80, v189
	ds_read_b128 v[236:239], v186 offset:32768
	v_exp_f32_e32 v235, v235
	v_pk_add_f32 v[170:171], v[170:171], v[232:233]
	s_nop 0
	v_pk_add_f32 v[170:171], v[170:171], v[234:235]
	s_waitcnt lgkmcnt(1)
	v_mfma_f32_32x32x16_bf16 v[80:95], v[240:243], v[116:119], v[80:95]
	ds_read_b128 v[240:243], v186 offset:40960
	v_add_f32_e32 v249, v170, v171
	v_mov_b32_e32 v170, v249
	s_nop 1
	s_waitcnt lgkmcnt(1)
	v_mfma_f32_32x32x16_bf16 v[64:79], v[236:239], v[120:123], v[64:79]
	ds_read_b128 v[236:239], v187 offset:32768
	v_permlane32_swap_b32_e32 v249, v170
	v_cvt_pk_bf16_f32 v204, v204, v205
	v_cvt_pk_bf16_f32 v205, v206, v207
	v_cvt_pk_bf16_f32 v206, v208, v209
	s_waitcnt lgkmcnt(1)
	v_mfma_f32_32x32x16_bf16 v[80:95], v[240:243], v[120:123], v[80:95]
	ds_read_b128 v[240:243], v187 offset:40960
	v_cvt_pk_bf16_f32 v207, v210, v211
	v_cvt_pk_bf16_f32 v208, v212, v213
	v_cvt_pk_bf16_f32 v209, v214, v215
	s_waitcnt lgkmcnt(1)
	v_mfma_f32_32x32x16_bf16 v[64:79], v[236:239], v[124:127], v[64:79]
	ds_read_b128 v[236:239], v188 offset:32768
	v_cvt_pk_bf16_f32 v210, v216, v217
	v_cvt_pk_bf16_f32 v211, v218, v219
	v_cvt_pk_bf16_f32 v212, v220, v221
	v_cvt_pk_bf16_f32 v213, v222, v223
	s_waitcnt lgkmcnt(1)
	v_mfma_f32_32x32x16_bf16 v[80:95], v[240:243], v[124:127], v[80:95]
	ds_read_b128 v[240:243], v188 offset:40960
	v_cvt_pk_bf16_f32 v214, v224, v225
	v_cvt_pk_bf16_f32 v215, v226, v227
	v_cvt_pk_bf16_f32 v216, v228, v229
	s_waitcnt lgkmcnt(1)
	v_mfma_f32_32x32x16_bf16 v[64:79], v[236:239], v[128:131], v[64:79]
	ds_read_b128 v[236:239], v189 offset:32768
	v_cvt_pk_bf16_f32 v217, v230, v231
	v_cvt_pk_bf16_f32 v218, v232, v233
	v_cvt_pk_bf16_f32 v219, v234, v235
	v_add_u32_e32 v165, s7, v178
	ds_read_b64_tr_b16 v[220:221], v165 offset:0
	ds_read_b64_tr_b16 v[222:223], v165 offset:2048
	ds_read_b64_tr_b16 v[224:225], v165 offset:4096
	ds_read_b64_tr_b16 v[226:227], v165 offset:6144
	ds_read_b64_tr_b16 v[228:229], v165 offset:8192
	ds_read_b64_tr_b16 v[230:231], v165 offset:10240
	ds_read_b64_tr_b16 v[232:233], v165 offset:12288
	ds_read_b64_tr_b16 v[234:235], v165 offset:14336
	v_permlane32_swap_b32_e32 v204, v206
	s_waitcnt lgkmcnt(1)
	v_mfma_f32_32x32x16_bf16 v[80:95], v[240:243], v[128:131], v[80:95]
	ds_read_b128 v[240:243], v189 offset:40960
	v_permlane32_swap_b32_e32 v205, v207
	v_permlane32_swap_b32_e32 v208, v210
	v_permlane32_swap_b32_e32 v209, v211
	v_permlane32_swap_b32_e32 v212, v214
	s_waitcnt lgkmcnt(1)
	v_mfma_f32_32x32x16_bf16 v[64:79], v[236:239], v[132:135], v[64:79]
	v_permlane32_swap_b32_e32 v213, v215
	v_permlane32_swap_b32_e32 v216, v218
	v_permlane32_swap_b32_e32 v217, v219
	s_waitcnt lgkmcnt(0)
	v_mfma_f32_32x32x16_bf16 v[80:95], v[240:243], v[132:135], v[80:95]
	v_add_f32_e32 v171, v249, v170
	v_fmac_f32_e32 v171, v185, v202
	v_mov_b32_e32 v185, v171
	s_waitcnt vmcnt(0)
	s_and_b64 vcc, exec, s[34:35]
	s_cbranch_vccz .Lat_nwo
	v_add_u32_e32 v200, s8, v180
	v_add_u32_e32 v201, s8, v181
	ds_write_b128 v200, v[96:99]
	ds_write_b128 v201, v[100:103]
	ds_write_b128 v182, v[136:139] offset:49152
	ds_write_b128 v182, v[140:143] offset:57344
.Lat_nwo:
	s_mov_b32 s9, s6
	s_mov_b32 s6, s7
	s_mov_b32 s7, s8
	s_mov_b32 s8, s9
	s_add_i32 s12, s12, 2
	s_cmp_lt_u32 s12, s18
	s_cbranch_scc1 .Lat_loop
	s_waitcnt lgkmcnt(6)
	v_mfma_f32_32x32x16_bf16 v[32:47], v[204:207], v[220:223], v[32:47]
	ds_read_b64_tr_b16 v[220:221], v165 offset:512
	ds_read_b64_tr_b16 v[222:223], v165 offset:2560
	s_waitcnt lgkmcnt(6)
	v_mfma_f32_32x32x16_bf16 v[32:47], v[208:211], v[224:227], v[32:47]
	ds_read_b64_tr_b16 v[224:225], v165 offset:4608
	ds_read_b64_tr_b16 v[226:227], v165 offset:6656
	s_waitcnt lgkmcnt(6)
	v_mfma_f32_32x32x16_bf16 v[32:47], v[212:215], v[228:231], v[32:47]
	ds_read_b64_tr_b16 v[228:229], v165 offset:8704
	ds_read_b64_tr_b16 v[230:231], v165 offset:10752
	s_waitcnt lgkmcnt(6)
	v_mfma_f32_32x32x16_bf16 v[32:47], v[216:219], v[232:235], v[32:47]
	ds_read_b64_tr_b16 v[232:233], v165 offset:12800
	ds_read_b64_tr_b16 v[234:235], v165 offset:14848
	s_waitcnt lgkmcnt(6)
	v_mfma_f32_32x32x16_bf16 v[48:63], v[204:207], v[220:223], v[48:63]
	ds_read_b64_tr_b16 v[220:221], v165 offset:1024
	ds_read_b64_tr_b16 v[222:223], v165 offset:3072
	s_waitcnt lgkmcnt(6)
	v_mfma_f32_32x32x16_bf16 v[48:63], v[208:211], v[224:227], v[48:63]
	ds_read_b64_tr_b16 v[224:225], v165 offset:5120
	ds_read_b64_tr_b16 v[226:227], v165 offset:7168
	s_waitcnt lgkmcnt(6)
	v_mfma_f32_32x32x16_bf16 v[48:63], v[212:215], v[228:231], v[48:63]
	ds_read_b64_tr_b16 v[228:229], v165 offset:9216
	ds_read_b64_tr_b16 v[230:231], v165 offset:11264
	s_waitcnt lgkmcnt(6)
	v_mfma_f32_32x32x16_bf16 v[48:63], v[216:219], v[232:235], v[48:63]
	ds_read_b64_tr_b16 v[232:233], v165 offset:13312
	ds_read_b64_tr_b16 v[234:235], v165 offset:15360
	s_waitcnt lgkmcnt(6)
	v_mfma_f32_32x32x16_bf16 v[16:31], v[204:207], v[220:223], v[16:31]
	ds_read_b64_tr_b16 v[220:221], v165 offset:1536
	ds_read_b64_tr_b16 v[222:223], v165 offset:3584
	s_waitcnt lgkmcnt(6)
	v_mfma_f32_32x32x16_bf16 v[16:31], v[208:211], v[224:227], v[16:31]
	ds_read_b64_tr_b16 v[224:225], v165 offset:5632
	ds_read_b64_tr_b16 v[226:227], v165 offset:7680
	s_waitcnt lgkmcnt(6)
	v_mfma_f32_32x32x16_bf16 v[16:31], v[212:215], v[228:231], v[16:31]
	ds_read_b64_tr_b16 v[228:229], v165 offset:9728
	ds_read_b64_tr_b16 v[230:231], v165 offset:11776
	s_waitcnt lgkmcnt(6)
	v_mfma_f32_32x32x16_bf16 v[16:31], v[216:219], v[232:235], v[16:31]
	ds_read_b64_tr_b16 v[232:233], v165 offset:13824
	ds_read_b64_tr_b16 v[234:235], v165 offset:15872
	s_waitcnt lgkmcnt(6)
	v_mfma_f32_32x32x16_bf16 v[0:15], v[204:207], v[220:223], v[0:15]
	s_waitcnt lgkmcnt(4)
	v_mfma_f32_32x32x16_bf16 v[0:15], v[208:211], v[224:227], v[0:15]
	s_waitcnt lgkmcnt(2)
	v_mfma_f32_32x32x16_bf16 v[0:15], v[212:215], v[228:231], v[0:15]
	s_waitcnt lgkmcnt(0)
	v_mfma_f32_32x32x16_bf16 v[0:15], v[216:219], v[232:235], v[0:15]
	s_nop 7
	s_nop 7
